# xprep loop body rewritten: 16 loads up front per iteration, shared modulation row, DPP reductions, saddr stores
# speedup vs baseline: 1.0042x; 1.0042x over previous
.LBB0_233:
	s_load_dwordx4 s[24:27], s[88:89], 0x0
	v_add_u32_e32 v37, -1, v31
	v_cmp_gt_i32_e64 s[40:41], s20, v37
	v_add_u32_e32 v39, 0xffffbfff, v31
	v_cmp_gt_i32_e64 s[38:39], s20, v31
	v_lshlrev_b32_e32 v128, 2, v30
	global_load_dwordx4 v[238:241], v[32:33], off
	global_load_dwordx4 v[242:245], v[32:33], off offset:1024
	global_load_dwordx4 v[246:249], v[32:33], off offset:2048
	global_load_dwordx4 v[228:231], v[32:33], off offset:3072
	v_lshl_add_u64 v[16:17], v[28:29], 0, s[62:63]
	v_cndmask_b32_e64 v17, 0, v17, s[40:41]
	v_cndmask_b32_e64 v16, v39, v16, s[40:41]
	s_waitcnt lgkmcnt(0)
	v_mov_b32_e32 v20, s27
	v_mov_b32_e32 v21, s25
	v_mov_b32_e32 v22, s26
	v_mov_b32_e32 v23, s24
	v_cndmask_b32_e64 v19, v20, v21, s[40:41]
	v_cndmask_b32_e64 v18, v22, v23, s[40:41]
	v_lshlrev_b64 v[16:17], 12, v[16:17]
	v_lshl_add_u64 v[16:17], v[18:19], 0, v[16:17]
	v_lshl_add_u64 v[16:17], v[16:17], 0, v[128:129]
	global_load_dwordx4 v[0:3], v[16:17], off
	global_load_dwordx4 v[4:7], v[16:17], off offset:1024
	global_load_dwordx4 v[8:11], v[16:17], off offset:2048
	global_load_dwordx4 v[12:15], v[16:17], off offset:3072
	v_lshl_add_u64 v[16:17], v[44:45], 0, s[62:63]
	v_add_u32_e32 v18, 0xffffc000, v31
	v_cndmask_b32_e64 v17, 0, v17, s[38:39]
	v_cndmask_b32_e64 v16, v18, v16, s[38:39]
	v_cndmask_b32_e64 v19, v20, v21, s[38:39]
	v_cndmask_b32_e64 v18, v22, v23, s[38:39]
	v_lshlrev_b64 v[16:17], 12, v[16:17]
	v_lshl_add_u64 v[16:17], v[18:19], 0, v[16:17]
	v_lshl_add_u64 v[16:17], v[16:17], 0, v[128:129]
	global_load_dwordx4 v[20:23], v[16:17], off offset:1024
	global_load_dwordx4 v[24:27], v[16:17], off offset:2048
	global_load_dwordx4 v[50:53], v[16:17], off offset:3072
	global_load_dwordx4 v[16:19], v[16:17], off
	v_lshrrev_b32_e32 v39, 3, v39
	v_ashrrev_i32_e32 v37, 11, v37
	v_add_u32_e32 v39, 8, v39
	v_cndmask_b32_e64 v56, v39, v37, s[40:41]
	v_mov_b64_e32 v[54:55], s[84:85]
	v_mad_i64_i32 v[54:55], s[8:9], v56, s21, v[54:55]
	v_lshl_add_u64 v[54:55], v[54:55], 0, s[94:95]
	v_lshl_add_u64 v[54:55], v[54:55], 0, v[128:129]
	global_load_dwordx4 v[58:61], v[54:55], off offset:1024
	global_load_dwordx4 v[62:65], v[54:55], off offset:2048
	global_load_dwordx4 v[234:237], v[54:55], off offset:3072
	global_load_dwordx4 v[54:57], v[54:55], off
	s_add_u32 s28, s84, s19
	s_addc_u32 s29, s85, 0
	s_add_u32 s30, s84, s46
	s_addc_u32 s31, s85, 0
	s_waitcnt vmcnt(0)
	v_pk_add_f32 v[54:55], v[54:55], 1.0 op_sel_hi:[1,0]
	v_pk_add_f32 v[56:57], v[56:57], 1.0 op_sel_hi:[1,0]
	v_pk_add_f32 v[58:59], v[58:59], 1.0 op_sel_hi:[1,0]
	v_pk_add_f32 v[60:61], v[60:61], 1.0 op_sel_hi:[1,0]
	v_pk_add_f32 v[62:63], v[62:63], 1.0 op_sel_hi:[1,0]
	v_pk_add_f32 v[64:65], v[64:65], 1.0 op_sel_hi:[1,0]
	v_pk_add_f32 v[234:235], v[234:235], 1.0 op_sel_hi:[1,0]
	v_pk_add_f32 v[236:237], v[236:237], 1.0 op_sel_hi:[1,0]
	v_mul_f32_e32 v250, v1, v1
	v_mul_f32_e32 v251, v3, v3
	v_fmac_f32_e32 v250, v0, v0
	v_fmac_f32_e32 v251, v2, v2
	v_pk_mul_f32 v[66:67], v[0:1], v[238:239]
	v_add_f32_e32 v68, v250, v251
	v_pk_mul_f32 v[250:251], v[2:3], v[240:241]
	v_pk_mul_f32 v[66:67], v[54:55], v[66:67]
	v_pk_mul_f32 v[250:251], v[56:57], v[250:251]
	v_cvt_pk_bf16_f32 v66, v66, v67
	v_cvt_pk_bf16_f32 v67, v250, v251
	global_store_dwordx2 v48, v[66:67], s[28:29] offset:0
	v_cvt_pk_bf16_f32 v0, v0, v1
	v_cvt_pk_bf16_f32 v1, v2, v3
	global_store_dwordx2 v48, v[0:1], s[30:31] offset:0
	v_mul_f32_e32 v250, v5, v5
	v_mul_f32_e32 v251, v7, v7
	v_fmac_f32_e32 v250, v4, v4
	v_fmac_f32_e32 v251, v6, v6
	v_pk_mul_f32 v[66:67], v[4:5], v[242:243]
	v_add_f32_e32 v250, v250, v251
	v_add_f32_e32 v68, v68, v250
	v_pk_mul_f32 v[250:251], v[6:7], v[244:245]
	v_pk_mul_f32 v[66:67], v[58:59], v[66:67]
	v_pk_mul_f32 v[250:251], v[60:61], v[250:251]
	v_cvt_pk_bf16_f32 v66, v66, v67
	v_cvt_pk_bf16_f32 v67, v250, v251
	global_store_dwordx2 v48, v[66:67], s[28:29] offset:512
	v_cvt_pk_bf16_f32 v4, v4, v5
	v_cvt_pk_bf16_f32 v5, v6, v7
	global_store_dwordx2 v48, v[4:5], s[30:31] offset:512
	v_mul_f32_e32 v250, v9, v9
	v_mul_f32_e32 v251, v11, v11
	v_fmac_f32_e32 v250, v8, v8
	v_fmac_f32_e32 v251, v10, v10
	v_pk_mul_f32 v[66:67], v[8:9], v[246:247]
	v_add_f32_e32 v250, v250, v251
	v_add_f32_e32 v68, v68, v250
	v_pk_mul_f32 v[250:251], v[10:11], v[248:249]
	v_pk_mul_f32 v[66:67], v[62:63], v[66:67]
	v_pk_mul_f32 v[250:251], v[64:65], v[250:251]
	v_cvt_pk_bf16_f32 v66, v66, v67
	v_cvt_pk_bf16_f32 v67, v250, v251
	global_store_dwordx2 v48, v[66:67], s[28:29] offset:1024
	v_cvt_pk_bf16_f32 v8, v8, v9
	v_cvt_pk_bf16_f32 v9, v10, v11
	global_store_dwordx2 v48, v[8:9], s[30:31] offset:1024
	v_mul_f32_e32 v250, v13, v13
	v_mul_f32_e32 v251, v15, v15
	v_fmac_f32_e32 v250, v12, v12
	v_fmac_f32_e32 v251, v14, v14
	v_pk_mul_f32 v[66:67], v[12:13], v[228:229]
	v_add_f32_e32 v250, v250, v251
	v_add_f32_e32 v68, v68, v250
	v_pk_mul_f32 v[250:251], v[14:15], v[230:231]
	v_pk_mul_f32 v[66:67], v[234:235], v[66:67]
	v_pk_mul_f32 v[250:251], v[236:237], v[250:251]
	v_cvt_pk_bf16_f32 v66, v66, v67
	v_cvt_pk_bf16_f32 v67, v250, v251
	global_store_dwordx2 v48, v[66:67], s[28:29] offset:1536
	v_cvt_pk_bf16_f32 v12, v12, v13
	v_cvt_pk_bf16_f32 v13, v14, v15
	global_store_dwordx2 v48, v[12:13], s[30:31] offset:1536
	s_nop 1
	v_add_f32_dpp v68, v68, v68 quad_perm:[1,0,3,2] row_mask:0xf bank_mask:0xf
	s_nop 1
	v_add_f32_dpp v68, v68, v68 quad_perm:[2,3,0,1] row_mask:0xf bank_mask:0xf
	s_nop 1
	v_add_f32_dpp v68, v68, v68 row_half_mirror row_mask:0xf bank_mask:0xf
	s_nop 1
	v_add_f32_dpp v68, v68, v68 row_mirror row_mask:0xf bank_mask:0xf
	s_nop 1
	v_add_f32_dpp v68, v68, v68 row_bcast:15 row_mask:0xa bank_mask:0xf
	s_nop 1
	v_add_f32_dpp v68, v68, v68 row_bcast:31 row_mask:0xc bank_mask:0xf
	s_mov_b64 s[38:39], exec
	s_lshl_b64 s[40:41], 1, 63
	s_mov_b64 exec, s[40:41]
	v_lshl_add_u64 v[66:67], s[84:85], 0, v[46:47]
	global_store_dword v[66:67], v68, off
	s_mov_b64 exec, s[38:39]
	v_mul_f32_e32 v250, v17, v17
	v_mul_f32_e32 v251, v19, v19
	v_fmac_f32_e32 v250, v16, v16
	v_fmac_f32_e32 v251, v18, v18
	v_pk_mul_f32 v[66:67], v[16:17], v[238:239]
	v_add_f32_e32 v68, v250, v251
	v_pk_mul_f32 v[250:251], v[18:19], v[240:241]
	v_pk_mul_f32 v[66:67], v[54:55], v[66:67]
	v_pk_mul_f32 v[250:251], v[56:57], v[250:251]
	v_cvt_pk_bf16_f32 v66, v66, v67
	v_cvt_pk_bf16_f32 v67, v250, v251
	global_store_dwordx2 v42, v[66:67], s[28:29] offset:2048
	v_cvt_pk_bf16_f32 v16, v16, v17
	v_cvt_pk_bf16_f32 v17, v18, v19
	global_store_dwordx2 v42, v[16:17], s[30:31] offset:2048
	v_mul_f32_e32 v250, v21, v21
	v_mul_f32_e32 v251, v23, v23
	v_fmac_f32_e32 v250, v20, v20
	v_fmac_f32_e32 v251, v22, v22
	v_pk_mul_f32 v[66:67], v[20:21], v[242:243]
	v_add_f32_e32 v250, v250, v251
	v_add_f32_e32 v68, v68, v250
	v_pk_mul_f32 v[250:251], v[22:23], v[244:245]
	v_pk_mul_f32 v[66:67], v[58:59], v[66:67]
	v_pk_mul_f32 v[250:251], v[60:61], v[250:251]
	v_cvt_pk_bf16_f32 v66, v66, v67
	v_cvt_pk_bf16_f32 v67, v250, v251
	global_store_dwordx2 v42, v[66:67], s[28:29] offset:2560
	v_cvt_pk_bf16_f32 v20, v20, v21
	v_cvt_pk_bf16_f32 v21, v22, v23
	global_store_dwordx2 v42, v[20:21], s[30:31] offset:2560
	v_mul_f32_e32 v250, v25, v25
	v_mul_f32_e32 v251, v27, v27
	v_fmac_f32_e32 v250, v24, v24
	v_fmac_f32_e32 v251, v26, v26
	v_pk_mul_f32 v[66:67], v[24:25], v[246:247]
	v_add_f32_e32 v250, v250, v251
	v_add_f32_e32 v68, v68, v250
	v_pk_mul_f32 v[250:251], v[26:27], v[248:249]
	v_pk_mul_f32 v[66:67], v[62:63], v[66:67]
	v_pk_mul_f32 v[250:251], v[64:65], v[250:251]
	v_cvt_pk_bf16_f32 v66, v66, v67
	v_cvt_pk_bf16_f32 v67, v250, v251
	global_store_dwordx2 v42, v[66:67], s[28:29] offset:3072
	v_cvt_pk_bf16_f32 v24, v24, v25
	v_cvt_pk_bf16_f32 v25, v26, v27
	global_store_dwordx2 v42, v[24:25], s[30:31] offset:3072
	v_mul_f32_e32 v250, v51, v51
	v_mul_f32_e32 v251, v53, v53
	v_fmac_f32_e32 v250, v50, v50
	v_fmac_f32_e32 v251, v52, v52
	v_pk_mul_f32 v[66:67], v[50:51], v[228:229]
	v_add_f32_e32 v250, v250, v251
	v_add_f32_e32 v68, v68, v250
	v_pk_mul_f32 v[250:251], v[52:53], v[230:231]
	v_pk_mul_f32 v[66:67], v[234:235], v[66:67]
	v_pk_mul_f32 v[250:251], v[236:237], v[250:251]
	v_cvt_pk_bf16_f32 v66, v66, v67
	v_cvt_pk_bf16_f32 v67, v250, v251
	global_store_dwordx2 v42, v[66:67], s[28:29] offset:3584
	v_cvt_pk_bf16_f32 v50, v50, v51
	v_cvt_pk_bf16_f32 v51, v52, v53
	global_store_dwordx2 v42, v[50:51], s[30:31] offset:3584
	s_nop 1
	v_add_f32_dpp v68, v68, v68 quad_perm:[1,0,3,2] row_mask:0xf bank_mask:0xf
	s_nop 1
	v_add_f32_dpp v68, v68, v68 quad_perm:[2,3,0,1] row_mask:0xf bank_mask:0xf
	s_nop 1
	v_add_f32_dpp v68, v68, v68 row_half_mirror row_mask:0xf bank_mask:0xf
	s_nop 1
	v_add_f32_dpp v68, v68, v68 row_mirror row_mask:0xf bank_mask:0xf
	s_nop 1
	v_add_f32_dpp v68, v68, v68 row_bcast:15 row_mask:0xa bank_mask:0xf
	s_nop 1
	v_add_f32_dpp v68, v68, v68 row_bcast:31 row_mask:0xc bank_mask:0xf
	s_mov_b64 s[38:39], exec
	s_lshl_b64 s[40:41], 1, 63
	s_mov_b64 exec, s[40:41]
	v_lshl_add_u64 v[66:67], s[84:85], 0, v[40:41]
	global_store_dword v[66:67], v68, off
	s_mov_b64 exec, s[38:39]
	s_mov_b64 s[8:9], exec
	s_branch .LBB0_232
